# final-norm token loop: norm-weight chunk loads 1..3 issued with chunk 0, per-chunk vmcnt drains dropped (f32 stores stream); stacked on v102
# baseline (speedup 1.0000x reference)
.LBB0_2122:
	v_lshl_add_u64 v[16:17], s[10:11], 0, v[12:13]
	global_load_dwordx2 v[18:19], v[16:17], off
	global_load_dwordx2 v[20:21], v[16:17], off offset:512
	global_load_dwordx2 v[22:23], v[16:17], off offset:1024
	global_load_dwordx2 v[24:25], v[16:17], off offset:1536
	global_load_dwordx4 v[46:49], v[4:5], off
	global_load_dwordx4 v[92:95], v[4:5], off offset:1024
	global_load_dwordx4 v[96:99], v[4:5], off offset:2048
	global_load_dwordx4 v[100:103], v[4:5], off offset:3072
	v_add_u32_e32 v3, s15, v2
	v_add_u32_e32 v26, s3, v2
	v_add_u32_e32 v16, s74, v2
	v_min_i32_e32 v28, 0x7fff, v3
	v_min_i32_e32 v30, 0x7fff, v26
	v_min_i32_e32 v32, 0x7fff, v16
	v_ashrrev_i32_e32 v29, 31, v28
	v_ashrrev_i32_e32 v31, 31, v30
	v_ashrrev_i32_e32 v33, 31, v32
	v_lshlrev_b64 v[28:29], 12, v[28:29]
	v_lshlrev_b64 v[30:31], 12, v[30:31]
	v_lshlrev_b64 v[32:33], 12, v[32:33]
	v_lshl_add_u64 v[52:53], v[6:7], 0, v[28:29]
	v_lshl_add_u64 v[54:55], v[6:7], 0, v[30:31]
	v_lshl_add_u64 v[56:57], v[6:7], 0, v[32:33]
	global_load_dwordx2 v[42:43], v[52:53], off
	global_load_dwordx2 v[40:41], v[52:53], off offset:512
	global_load_dwordx2 v[38:39], v[52:53], off offset:1024
	global_load_dwordx2 v[36:37], v[52:53], off offset:1536
	global_load_dwordx2 v[34:35], v[54:55], off
	global_load_dwordx2 v[32:33], v[54:55], off offset:512
	global_load_dwordx2 v[30:31], v[54:55], off offset:1024
	global_load_dwordx2 v[28:29], v[54:55], off offset:1536
	v_lshl_add_u64 v[50:51], s[10:11], 0, v[14:15]
	s_waitcnt vmcnt(0)
	v_and_b32_e32 v53, 0xffff0000, v18
	v_and_b32_e32 v59, 0xffff0000, v20
	v_lshlrev_b32_e32 v52, 16, v18
	v_lshlrev_b32_e32 v58, 16, v20
	v_lshlrev_b32_e32 v60, 16, v21
	v_and_b32_e32 v61, 0xffff0000, v21
	v_and_b32_e32 v63, 0xffff0000, v22
	v_and_b32_e32 v67, 0xffff0000, v24
	v_mov_b32_e32 v20, v59
	v_mov_b32_e32 v21, v53
	v_lshlrev_b32_e32 v54, 16, v19
	v_and_b32_e32 v55, 0xffff0000, v19
	v_lshlrev_b32_e32 v62, 16, v22
	v_lshlrev_b32_e32 v66, 16, v24
	v_mov_b32_e32 v18, v58
	v_mov_b32_e32 v19, v52
	v_mov_b32_e32 v72, v67
	v_mov_b32_e32 v73, v63
	v_pk_mul_f32 v[20:21], v[20:21], v[20:21]
	v_lshlrev_b32_e32 v64, 16, v23
	v_and_b32_e32 v65, 0xffff0000, v23
	v_lshlrev_b32_e32 v68, 16, v25
	v_mov_b32_e32 v22, v60
	v_mov_b32_e32 v23, v54
	v_mov_b32_e32 v70, v66
	v_mov_b32_e32 v71, v62
	v_pk_mul_f32 v[72:73], v[72:73], v[72:73]
	v_pk_fma_f32 v[18:19], v[18:19], v[18:19], v[20:21]
	v_and_b32_e32 v69, 0xffff0000, v25
	v_mov_b32_e32 v24, v61
	v_mov_b32_e32 v25, v55
	v_mov_b32_e32 v74, v68
	v_mov_b32_e32 v75, v64
	v_pk_fma_f32 v[20:21], v[70:71], v[70:71], v[72:73]
	v_pk_fma_f32 v[18:19], v[22:23], v[22:23], v[18:19]
	v_mov_b32_e32 v76, v69
	v_mov_b32_e32 v77, v65
	v_pk_fma_f32 v[20:21], v[74:75], v[74:75], v[20:21]
	v_pk_fma_f32 v[18:19], v[24:25], v[24:25], v[18:19]
	v_pk_fma_f32 v[20:21], v[76:77], v[76:77], v[20:21]
	v_add_f32_e32 v0, v18, v19
	v_add_f32_e32 v0, v21, v0
	v_add_f32_e32 v0, v20, v0
	s_nop 1
	v_add_f32_dpp v0, v0, v0 quad_perm:[1,0,3,2] row_mask:0xf bank_mask:0xf bound_ctrl:1
	s_nop 1
	v_add_f32_dpp v0, v0, v0 quad_perm:[2,3,0,1] row_mask:0xf bank_mask:0xf bound_ctrl:1
	s_nop 1
	v_add_f32_dpp v0, v0, v0 row_half_mirror row_mask:0xf bank_mask:0xf bound_ctrl:1
	s_nop 1
	v_add_f32_dpp v0, v0, v0 row_mirror row_mask:0xf bank_mask:0xf bound_ctrl:1
	s_nop 0
	v_readlane_b32 s21, v0, 16
	v_readlane_b32 s22, v0, 48
	v_readlane_b32 s12, v0, 0
	v_readlane_b32 s13, v0, 32
	v_mov_b32_e32 v18, s21
	v_mov_b32_e32 v19, s22
	v_pk_add_f32 v[18:19], s[12:13], v[18:19]
	s_nop 0
	v_add_f32_e32 v0, v18, v19
	v_fmamk_f32 v0, v0, 0x3a800000, v44
	v_mul_f32_e32 v17, 0x4b800000, v0
	v_cmp_gt_f32_e32 vcc, s20, v0
	global_load_dwordx2 v[24:25], v[56:57], off
	global_load_dwordx2 v[22:23], v[56:57], off offset:512
	global_load_dwordx2 v[20:21], v[56:57], off offset:1024
	global_load_dwordx2 v[18:19], v[56:57], off offset:1536
	v_cndmask_b32_e32 v0, v0, v17, vcc
	v_rsq_f32_e32 v0, v0
	s_nop 0
	v_mul_f32_e32 v17, 0x45800000, v0
	v_cndmask_b32_e32 v0, v0, v17, vcc
	v_pk_mul_f32 v[52:53], v[0:1], v[52:53] op_sel_hi:[0,1]
	v_pk_mul_f32 v[54:55], v[0:1], v[54:55] op_sel_hi:[0,1]
	s_waitcnt lgkmcnt(0)
	v_pk_mul_f32 v[46:47], v[46:47], v[52:53]
	v_pk_mul_f32 v[48:49], v[48:49], v[54:55]
	global_store_dwordx4 v[50:51], v[46:49], off
	v_pk_mul_f32 v[52:53], v[0:1], v[58:59] op_sel_hi:[0,1]
	v_pk_mul_f32 v[54:55], v[0:1], v[60:61] op_sel_hi:[0,1]
	v_cmp_gt_i32_e32 vcc, s18, v3
	s_waitcnt lgkmcnt(0)
	v_mov_b32_e32 v46, v92
	v_mov_b32_e32 v47, v93
	v_mov_b32_e32 v48, v94
	v_mov_b32_e32 v49, v95
	v_pk_mul_f32 v[46:47], v[46:47], v[52:53]
	v_pk_mul_f32 v[48:49], v[48:49], v[54:55]
	global_store_dwordx4 v[50:51], v[46:49], off offset:1024
	v_pk_mul_f32 v[52:53], v[0:1], v[62:63] op_sel_hi:[0,1]
	v_pk_mul_f32 v[54:55], v[0:1], v[64:65] op_sel_hi:[0,1]
	s_waitcnt lgkmcnt(0)
	v_mov_b32_e32 v46, v96
	v_mov_b32_e32 v47, v97
	v_mov_b32_e32 v48, v98
	v_mov_b32_e32 v49, v99
	v_pk_mul_f32 v[46:47], v[52:53], v[46:47]
	v_pk_mul_f32 v[48:49], v[54:55], v[48:49]
	global_store_dwordx4 v[50:51], v[46:49], off offset:2048
	v_pk_mul_f32 v[52:53], v[0:1], v[66:67] op_sel_hi:[0,1]
	v_pk_mul_f32 v[54:55], v[0:1], v[68:69] op_sel_hi:[0,1]
	s_waitcnt lgkmcnt(0)
	v_mov_b32_e32 v46, v100
	v_mov_b32_e32 v47, v101
	v_mov_b32_e32 v48, v102
	v_mov_b32_e32 v49, v103
	v_pk_mul_f32 v[46:47], v[52:53], v[46:47]
	v_pk_mul_f32 v[48:49], v[54:55], v[48:49]
	global_store_dwordx4 v[50:51], v[46:49], off offset:3072
	s_and_saveexec_b64 s[12:13], vcc
	s_cbranch_execz .LBB0_2121
	global_load_dwordx4 v[46:49], v[4:5], off
	global_load_dwordx4 v[92:95], v[4:5], off offset:1024
	global_load_dwordx4 v[96:99], v[4:5], off offset:2048
	global_load_dwordx4 v[100:103], v[4:5], off offset:3072
	v_and_b32_e32 v51, 0xffff0000, v42
	v_and_b32_e32 v53, 0xffff0000, v40
	v_lshlrev_b32_e32 v50, 16, v42
	v_lshlrev_b32_e32 v52, 16, v40
	v_lshlrev_b32_e32 v54, 16, v38
	v_and_b32_e32 v55, 0xffff0000, v38
	v_lshlrev_b32_e32 v56, 16, v39
	v_and_b32_e32 v57, 0xffff0000, v39
	v_and_b32_e32 v59, 0xffff0000, v36
	v_mov_b32_e32 v38, v51
	v_mov_b32_e32 v39, v53
	v_lshlrev_b32_e32 v42, 16, v43
	v_lshlrev_b32_e32 v40, 16, v41
	v_lshlrev_b32_e32 v58, 16, v36
	v_lshlrev_b32_e32 v60, 16, v37
	v_and_b32_e32 v61, 0xffff0000, v37
	v_mov_b32_e32 v36, v50
	v_mov_b32_e32 v37, v52
	v_mov_b32_e32 v68, v55
	v_mov_b32_e32 v69, v59
	v_pk_mul_f32 v[38:39], v[38:39], v[38:39]
	v_and_b32_e32 v43, 0xffff0000, v43
	v_and_b32_e32 v41, 0xffff0000, v41
	v_mov_b32_e32 v62, v42
	v_mov_b32_e32 v63, v40
	v_mov_b32_e32 v66, v54
	v_mov_b32_e32 v67, v58
	v_pk_mul_f32 v[68:69], v[68:69], v[68:69]
	v_pk_fma_f32 v[36:37], v[36:37], v[36:37], v[38:39]
	v_mov_b32_e32 v64, v43
	v_mov_b32_e32 v65, v41
	v_mov_b32_e32 v70, v56
	v_mov_b32_e32 v71, v60
	v_pk_fma_f32 v[38:39], v[66:67], v[66:67], v[68:69]
	v_pk_fma_f32 v[36:37], v[62:63], v[62:63], v[36:37]
	v_mov_b32_e32 v72, v57
	v_mov_b32_e32 v73, v61
	v_pk_fma_f32 v[38:39], v[70:71], v[70:71], v[38:39]
	v_pk_fma_f32 v[36:37], v[64:65], v[64:65], v[36:37]
	v_pk_fma_f32 v[38:39], v[72:73], v[72:73], v[38:39]
	v_add_f32_e32 v0, v36, v37
	v_add_f32_e32 v0, v0, v38
	v_add_f32_e32 v0, v0, v39
	v_lshl_add_u64 v[62:63], s[10:11], 0, v[10:11]
	s_nop 0
	v_add_f32_dpp v0, v0, v0 quad_perm:[1,0,3,2] row_mask:0xf bank_mask:0xf bound_ctrl:1
	s_nop 1
	v_add_f32_dpp v0, v0, v0 quad_perm:[2,3,0,1] row_mask:0xf bank_mask:0xf bound_ctrl:1
	s_nop 1
	v_add_f32_dpp v0, v0, v0 row_half_mirror row_mask:0xf bank_mask:0xf bound_ctrl:1
	s_nop 1
	v_add_f32_dpp v0, v0, v0 row_mirror row_mask:0xf bank_mask:0xf bound_ctrl:1
	s_nop 0
	v_readlane_b32 s21, v0, 16
	v_readlane_b32 s24, v0, 48
	v_readlane_b32 s22, v0, 0
	v_readlane_b32 s23, v0, 32
	v_mov_b32_e32 v36, s21
	v_mov_b32_e32 v37, s24
	v_pk_add_f32 v[36:37], s[22:23], v[36:37]
	s_nop 0
	v_add_f32_e32 v0, v36, v37
	v_fmamk_f32 v0, v0, 0x3a800000, v44
	v_mul_f32_e32 v3, 0x4b800000, v0
	v_cmp_gt_f32_e32 vcc, s20, v0
	s_nop 1
	v_cndmask_b32_e32 v0, v0, v3, vcc
	v_rsq_f32_e32 v0, v0
	s_nop 0
	v_mul_f32_e32 v3, 0x45800000, v0
	v_cndmask_b32_e32 v0, v0, v3, vcc
	v_pk_mul_f32 v[36:37], v[0:1], v[50:51] op_sel_hi:[0,1]
	v_pk_mul_f32 v[38:39], v[0:1], v[42:43] op_sel_hi:[0,1]
	s_waitcnt vmcnt(0) lgkmcnt(0)
	v_pk_mul_f32 v[36:37], v[46:47], v[36:37]
	v_pk_mul_f32 v[38:39], v[48:49], v[38:39]
	global_store_dwordx4 v[62:63], v[36:39], off
	v_pk_mul_f32 v[42:43], v[0:1], v[52:53] op_sel_hi:[0,1]
	v_pk_mul_f32 v[40:41], v[0:1], v[40:41] op_sel_hi:[0,1]
	v_cmp_gt_i32_e32 vcc, s18, v26
	s_waitcnt lgkmcnt(0)
	v_mov_b32_e32 v36, v92
	v_mov_b32_e32 v37, v93
	v_mov_b32_e32 v38, v94
	v_mov_b32_e32 v39, v95
	v_pk_mul_f32 v[36:37], v[36:37], v[42:43]
	v_pk_mul_f32 v[38:39], v[38:39], v[40:41]
	global_store_dwordx4 v[62:63], v[36:39], off offset:1024
	v_pk_mul_f32 v[40:41], v[0:1], v[54:55] op_sel_hi:[0,1]
	v_pk_mul_f32 v[42:43], v[0:1], v[56:57] op_sel_hi:[0,1]
	s_waitcnt lgkmcnt(0)
	v_mov_b32_e32 v36, v96
	v_mov_b32_e32 v37, v97
	v_mov_b32_e32 v38, v98
	v_mov_b32_e32 v39, v99
	v_pk_mul_f32 v[36:37], v[40:41], v[36:37]
	v_pk_mul_f32 v[38:39], v[42:43], v[38:39]
	global_store_dwordx4 v[62:63], v[36:39], off offset:2048
	v_pk_mul_f32 v[40:41], v[0:1], v[58:59] op_sel_hi:[0,1]
	v_pk_mul_f32 v[42:43], v[0:1], v[60:61] op_sel_hi:[0,1]
	s_waitcnt lgkmcnt(0)
	v_mov_b32_e32 v36, v100
	v_mov_b32_e32 v37, v101
	v_mov_b32_e32 v38, v102
	v_mov_b32_e32 v39, v103
	v_pk_mul_f32 v[36:37], v[40:41], v[36:37]
	v_pk_mul_f32 v[38:39], v[42:43], v[38:39]
	global_store_dwordx4 v[62:63], v[36:39], off offset:3072
	s_and_b64 exec, exec, vcc
	s_cbranch_execz .LBB0_2121
	global_load_dwordx4 v[36:39], v[4:5], off
	global_load_dwordx4 v[92:95], v[4:5], off offset:1024
	global_load_dwordx4 v[96:99], v[4:5], off offset:2048
	global_load_dwordx4 v[100:103], v[4:5], off offset:3072
	v_and_b32_e32 v41, 0xffff0000, v34
	v_and_b32_e32 v43, 0xffff0000, v32
	v_lshlrev_b32_e32 v40, 16, v34
	v_lshlrev_b32_e32 v42, 16, v32
	v_and_b32_e32 v47, 0xffff0000, v30
	v_and_b32_e32 v49, 0xffff0000, v28
	v_mov_b32_e32 v52, v41
	v_mov_b32_e32 v53, v43
	v_lshlrev_b32_e32 v34, 16, v35
	v_lshlrev_b32_e32 v32, 16, v33
	v_lshlrev_b32_e32 v46, 16, v30
	v_lshlrev_b32_e32 v48, 16, v28
	v_lshlrev_b32_e32 v50, 16, v29
	v_and_b32_e32 v51, 0xffff0000, v29
	v_mov_b32_e32 v28, v40
	v_mov_b32_e32 v29, v42
	v_mov_b32_e32 v60, v47
	v_mov_b32_e32 v61, v49
	v_pk_mul_f32 v[52:53], v[52:53], v[52:53]
	v_and_b32_e32 v35, 0xffff0000, v35
	v_and_b32_e32 v33, 0xffff0000, v33
	v_lshlrev_b32_e32 v30, 16, v31
	v_mov_b32_e32 v54, v34
	v_mov_b32_e32 v55, v32
	v_mov_b32_e32 v58, v46
	v_mov_b32_e32 v59, v48
	v_pk_mul_f32 v[60:61], v[60:61], v[60:61]
	v_pk_fma_f32 v[28:29], v[28:29], v[28:29], v[52:53]
	v_and_b32_e32 v31, 0xffff0000, v31
	v_mov_b32_e32 v56, v35
	v_mov_b32_e32 v57, v33
	v_mov_b32_e32 v62, v30
	v_mov_b32_e32 v63, v50
	v_pk_fma_f32 v[52:53], v[58:59], v[58:59], v[60:61]
	v_pk_fma_f32 v[28:29], v[54:55], v[54:55], v[28:29]
	v_mov_b32_e32 v64, v31
	v_mov_b32_e32 v65, v51
	v_pk_fma_f32 v[52:53], v[62:63], v[62:63], v[52:53]
	v_pk_fma_f32 v[28:29], v[56:57], v[56:57], v[28:29]
	v_pk_fma_f32 v[52:53], v[64:65], v[64:65], v[52:53]
	v_add_f32_e32 v0, v28, v29
	v_add_f32_e32 v0, v0, v52
	v_add_f32_e32 v0, v0, v53
	v_ashrrev_i32_e32 v27, 31, v26
	v_lshlrev_b64 v[26:27], 12, v[26:27]
	v_add_f32_dpp v0, v0, v0 quad_perm:[1,0,3,2] row_mask:0xf bank_mask:0xf bound_ctrl:1
	v_lshl_add_u64 v[52:53], v[8:9], 0, v[26:27]
	s_nop 0
	v_add_f32_dpp v0, v0, v0 quad_perm:[2,3,0,1] row_mask:0xf bank_mask:0xf bound_ctrl:1
	s_nop 1
	v_add_f32_dpp v0, v0, v0 row_half_mirror row_mask:0xf bank_mask:0xf bound_ctrl:1
	s_nop 1
	v_add_f32_dpp v0, v0, v0 row_mirror row_mask:0xf bank_mask:0xf bound_ctrl:1
	s_nop 0
	v_readlane_b32 s21, v0, 16
	v_readlane_b32 s24, v0, 48
	v_readlane_b32 s22, v0, 0
	v_readlane_b32 s23, v0, 32
	v_mov_b32_e32 v28, s21
	v_mov_b32_e32 v29, s24
	v_pk_add_f32 v[28:29], s[22:23], v[28:29]
	s_nop 0
	v_add_f32_e32 v0, v28, v29
	v_fmamk_f32 v0, v0, 0x3a800000, v44
	v_mul_f32_e32 v3, 0x4b800000, v0
	v_cmp_gt_f32_e32 vcc, s20, v0
	s_nop 1
	v_cndmask_b32_e32 v0, v0, v3, vcc
	v_rsq_f32_e32 v0, v0
	s_nop 0
	v_mul_f32_e32 v3, 0x45800000, v0
	v_cndmask_b32_e32 v0, v0, v3, vcc
	v_pk_mul_f32 v[26:27], v[0:1], v[40:41] op_sel_hi:[0,1]
	v_pk_mul_f32 v[28:29], v[0:1], v[34:35] op_sel_hi:[0,1]
	s_waitcnt vmcnt(0) lgkmcnt(0)
	v_pk_mul_f32 v[26:27], v[36:37], v[26:27]
	v_pk_mul_f32 v[28:29], v[38:39], v[28:29]
	global_store_dwordx4 v[52:53], v[26:29], off
	v_pk_mul_f32 v[34:35], v[0:1], v[42:43] op_sel_hi:[0,1]
	v_pk_mul_f32 v[32:33], v[0:1], v[32:33] op_sel_hi:[0,1]
	v_pk_mul_f32 v[30:31], v[0:1], v[30:31] op_sel_hi:[0,1]
	v_cmp_gt_i32_e32 vcc, s18, v16
	s_waitcnt lgkmcnt(0)
	v_mov_b32_e32 v26, v92
	v_mov_b32_e32 v27, v93
	v_mov_b32_e32 v28, v94
	v_mov_b32_e32 v29, v95
	v_pk_mul_f32 v[26:27], v[26:27], v[34:35]
	v_pk_mul_f32 v[28:29], v[28:29], v[32:33]
	global_store_dwordx4 v[52:53], v[26:29], off offset:1024
	v_pk_mul_f32 v[32:33], v[0:1], v[46:47] op_sel_hi:[0,1]
	s_waitcnt lgkmcnt(0)
	v_mov_b32_e32 v26, v96
	v_mov_b32_e32 v27, v97
	v_mov_b32_e32 v28, v98
	v_mov_b32_e32 v29, v99
	v_pk_mul_f32 v[26:27], v[32:33], v[26:27]
	v_pk_mul_f32 v[28:29], v[30:31], v[28:29]
	global_store_dwordx4 v[52:53], v[26:29], off offset:2048
	v_pk_mul_f32 v[30:31], v[0:1], v[48:49] op_sel_hi:[0,1]
	v_pk_mul_f32 v[32:33], v[0:1], v[50:51] op_sel_hi:[0,1]
	s_waitcnt lgkmcnt(0)
	v_mov_b32_e32 v26, v100
	v_mov_b32_e32 v27, v101
	v_mov_b32_e32 v28, v102
	v_mov_b32_e32 v29, v103
	v_pk_mul_f32 v[26:27], v[30:31], v[26:27]
	v_pk_mul_f32 v[28:29], v[32:33], v[28:29]
	global_store_dwordx4 v[52:53], v[26:29], off offset:3072
	s_and_b64 exec, exec, vcc
	s_cbranch_execz .LBB0_2121
	global_load_dwordx4 v[26:29], v[4:5], off
	global_load_dwordx4 v[92:95], v[4:5], off offset:1024
	global_load_dwordx4 v[96:99], v[4:5], off offset:2048
	global_load_dwordx4 v[100:103], v[4:5], off offset:3072
	v_and_b32_e32 v31, 0xffff0000, v24
	v_and_b32_e32 v33, 0xffff0000, v22
	v_lshlrev_b32_e32 v30, 16, v24
	v_lshlrev_b32_e32 v32, 16, v22
	v_and_b32_e32 v35, 0xffff0000, v20
	v_and_b32_e32 v37, 0xffff0000, v18
	v_mov_b32_e32 v40, v31
	v_mov_b32_e32 v41, v33
	v_lshlrev_b32_e32 v24, 16, v25
	v_lshlrev_b32_e32 v22, 16, v23
	v_lshlrev_b32_e32 v34, 16, v20
	v_lshlrev_b32_e32 v36, 16, v18
	v_lshlrev_b32_e32 v38, 16, v19
	v_and_b32_e32 v39, 0xffff0000, v19
	v_mov_b32_e32 v18, v30
	v_mov_b32_e32 v19, v32
	v_mov_b32_e32 v50, v35
	v_mov_b32_e32 v51, v37
	v_pk_mul_f32 v[40:41], v[40:41], v[40:41]
	v_and_b32_e32 v25, 0xffff0000, v25
	v_and_b32_e32 v23, 0xffff0000, v23
	v_lshlrev_b32_e32 v20, 16, v21
	v_mov_b32_e32 v42, v24
	v_mov_b32_e32 v43, v22
	v_mov_b32_e32 v48, v34
	v_mov_b32_e32 v49, v36
	v_pk_mul_f32 v[50:51], v[50:51], v[50:51]
	v_pk_fma_f32 v[18:19], v[18:19], v[18:19], v[40:41]
	v_and_b32_e32 v21, 0xffff0000, v21
	v_mov_b32_e32 v46, v25
	v_mov_b32_e32 v47, v23
	v_mov_b32_e32 v52, v20
	v_mov_b32_e32 v53, v38
	v_pk_fma_f32 v[40:41], v[48:49], v[48:49], v[50:51]
	v_pk_fma_f32 v[18:19], v[42:43], v[42:43], v[18:19]
	v_mov_b32_e32 v54, v21
	v_mov_b32_e32 v55, v39
	v_pk_fma_f32 v[40:41], v[52:53], v[52:53], v[40:41]
	v_pk_fma_f32 v[18:19], v[46:47], v[46:47], v[18:19]
	v_pk_fma_f32 v[40:41], v[54:55], v[54:55], v[40:41]
	v_add_f32_e32 v0, v18, v19
	v_add_f32_e32 v0, v0, v40
	v_add_f32_e32 v0, v0, v41
	v_ashrrev_i32_e32 v17, 31, v16
	v_lshlrev_b64 v[16:17], 12, v[16:17]
	v_add_f32_dpp v0, v0, v0 quad_perm:[1,0,3,2] row_mask:0xf bank_mask:0xf bound_ctrl:1
	v_lshl_add_u64 v[40:41], v[8:9], 0, v[16:17]
	s_nop 0
	v_add_f32_dpp v0, v0, v0 quad_perm:[2,3,0,1] row_mask:0xf bank_mask:0xf bound_ctrl:1
	s_nop 1
	v_add_f32_dpp v0, v0, v0 row_half_mirror row_mask:0xf bank_mask:0xf bound_ctrl:1
	s_nop 1
	v_add_f32_dpp v0, v0, v0 row_mirror row_mask:0xf bank_mask:0xf bound_ctrl:1
	s_nop 0
	v_readlane_b32 s21, v0, 16
	v_readlane_b32 s24, v0, 48
	v_readlane_b32 s22, v0, 0
	v_readlane_b32 s23, v0, 32
	v_mov_b32_e32 v18, s21
	v_mov_b32_e32 v19, s24
	v_pk_add_f32 v[18:19], s[22:23], v[18:19]
	s_nop 0
	v_add_f32_e32 v0, v18, v19
	v_fmamk_f32 v0, v0, 0x3a800000, v44
	v_mul_f32_e32 v3, 0x4b800000, v0
	v_cmp_gt_f32_e32 vcc, s20, v0
	s_nop 1
	v_cndmask_b32_e32 v0, v0, v3, vcc
	v_rsq_f32_e32 v0, v0
	s_nop 0
	v_mul_f32_e32 v3, 0x45800000, v0
	v_cndmask_b32_e32 v0, v0, v3, vcc
	v_pk_mul_f32 v[16:17], v[0:1], v[30:31] op_sel_hi:[0,1]
	v_pk_mul_f32 v[18:19], v[0:1], v[24:25] op_sel_hi:[0,1]
	s_waitcnt vmcnt(0) lgkmcnt(0)
	v_pk_mul_f32 v[16:17], v[26:27], v[16:17]
	v_pk_mul_f32 v[18:19], v[28:29], v[18:19]
	global_store_dwordx4 v[40:41], v[16:19], off
	v_pk_mul_f32 v[24:25], v[0:1], v[32:33] op_sel_hi:[0,1]
	v_pk_mul_f32 v[22:23], v[0:1], v[22:23] op_sel_hi:[0,1]
	v_pk_mul_f32 v[20:21], v[0:1], v[20:21] op_sel_hi:[0,1]
	s_waitcnt lgkmcnt(0)
	v_mov_b32_e32 v16, v92
	v_mov_b32_e32 v17, v93
	v_mov_b32_e32 v18, v94
	v_mov_b32_e32 v19, v95
	v_pk_mul_f32 v[16:17], v[16:17], v[24:25]
	v_pk_mul_f32 v[18:19], v[18:19], v[22:23]
	global_store_dwordx4 v[40:41], v[16:19], off offset:1024
	v_pk_mul_f32 v[22:23], v[0:1], v[34:35] op_sel_hi:[0,1]
	s_waitcnt lgkmcnt(0)
	v_mov_b32_e32 v16, v96
	v_mov_b32_e32 v17, v97
	v_mov_b32_e32 v18, v98
	v_mov_b32_e32 v19, v99
	v_pk_mul_f32 v[16:17], v[22:23], v[16:17]
	v_pk_mul_f32 v[18:19], v[20:21], v[18:19]
	global_store_dwordx4 v[40:41], v[16:19], off offset:2048
	v_pk_mul_f32 v[20:21], v[0:1], v[36:37] op_sel_hi:[0,1]
	v_pk_mul_f32 v[22:23], v[0:1], v[38:39] op_sel_hi:[0,1]
	s_waitcnt lgkmcnt(0)
	v_mov_b32_e32 v16, v100
	v_mov_b32_e32 v17, v101
	v_mov_b32_e32 v18, v102
	v_mov_b32_e32 v19, v103
	v_pk_mul_f32 v[16:17], v[20:21], v[16:17]
	v_pk_mul_f32 v[18:19], v[22:23], v[18:19]
	global_store_dwordx4 v[40:41], v[16:19], off offset:3072
	s_branch .LBB0_2121
